# FoX: next unit's first-stage prologue loads (Q frags, diagonal K rows, cumlog, totals/norms) prefetched at the current unit's epilogue start
# baseline (speedup 1.0000x reference)
_Z8yoco_fwd4Args:
	s_load_dwordx2 s[4:5], s[0:1], 0x80
	s_mov_b32 s100, -1
	v_writelane_b32 v241, s100, 36
	s_mov_b32 s23, s2
	s_add_u32 s2, s0, 0x80
	v_and_b32_e32 v1, 0x3ff, v0
	v_cmp_gt_u32_e32 vcc, 2, v1
	s_waitcnt lgkmcnt(0)
	v_writelane_b32 v243, s4, 0
	v_readfirstlane_b32 s36, v1
	s_nop 0
	v_writelane_b32 v243, s5, 1
	v_writelane_b32 v243, s0, 2
	s_addc_u32 s3, s1, 0
	s_nop 0
	v_writelane_b32 v243, s1, 3
	v_writelane_b32 v243, s2, 4
	s_nop 1
	v_writelane_b32 v243, s3, 5
	s_and_saveexec_b64 s[2:3], vcc
	v_lshl_add_u32 v2, v1, 2, 0
	v_add_u32_e32 v2, 0x23fc0, v2
	v_mov_b32_e32 v3, 0
	ds_write_b32 v2, v3
	s_or_b64 exec, exec, s[2:3]
	v_readlane_b32 s0, v243, 2
	v_readlane_b32 s1, v243, 3
	s_load_dwordx2 s[44:45], s[0:1], 0x68
	s_waitcnt lgkmcnt(0)
	s_barrier
	s_getreg_b32 s0, hwreg(HW_REG_XCC_ID, 0, 4)
	s_mov_b32 s38, 0
	v_cmp_eq_u32_e64 s[4:5], 0, v1
	s_mov_b64 s[2:3], exec
	s_nop 0
	v_writelane_b32 v243, s4, 6
	s_nop 1
	v_writelane_b32 v243, s5, 7
	s_and_b64 s[4:5], s[2:3], s[4:5]
	s_mov_b64 exec, s[4:5]
	s_cbranch_execz .LBB0_5
	s_mov_b64 s[4:5], exec
	v_mbcnt_lo_u32_b32 v2, s4, 0
	v_mbcnt_hi_u32_b32 v2, s5, v2
	v_cmp_eq_u32_e32 vcc, 0, v2
	s_and_b64 s[6:7], exec, vcc
	s_mov_b64 exec, s[6:7]
	s_cbranch_execz .LBB0_5
	s_lshl_b32 s0, s0, 8
	s_and_b32 s0, s0, 0xf00
	s_add_u32 s0, s44, s0
	s_addc_u32 s1, s45, 0
	s_bcnt1_i32_b64 s4, s[4:5]
	v_mov_b32_e32 v2, 0x102000
	v_mov_b32_e32 v3, s4
	global_atomic_add v2, v3, s[0:1] offset:1024

.LBB0_263:
	v_readlane_b32 s100, v241, 36
	s_cmp_eq_u32 s100, s1
	s_cselect_b32 s100, 1, 0
	s_cmp_lg_u32 s1, -1
	s_cselect_b64 s[6:7], -1, 0
	s_cmp_eq_u32 s1, -1
	s_cbranch_scc1 .LBB0_265
	s_lshr_b32 s8, s1, 5
	s_and_b32 s8, s8, 0x7fffff0
	s_bfe_u32 s9, s1, 0x40003
	s_or_b32 s40, s8, s9
	s_lshr_b32 s8, s1, 4
	s_and_b32 s8, s8, 24
	s_xor_b32 s8, s8, 31
	s_and_b32 s1, s1, 7
	s_sub_i32 s99, s8, s1
.LBB0_265:
	s_andn2_b64 vcc, exec, s[6:7]
	s_cbranch_vccnz .LBB0_268
	s_ashr_i32 s41, s40, 31
	s_lshr_b32 s1, s41, 28
	s_add_i32 s1, s40, s1
	s_ashr_i32 s30, s1, 4
	v_mbcnt_lo_u32_b32 v32, -1, 0
	v_mbcnt_hi_u32_b32 v32, -1, v32
	s_and_b32 s1, s1, 0x3fffff0
	v_add_u32_e32 v181, s36, v32
	s_ashr_i32 s31, s30, 31
	v_readfirstlane_b32 s34, v181
	s_lshl_b32 s10, s99, 8
	s_sub_i32 s1, s40, s1
	s_ashr_i32 s69, s34, 6
	s_lshl_b64 s[6:7], s[30:31], 13
	s_ashr_i32 s11, s10, 31
	s_add_u32 s6, s6, s10
	s_addc_u32 s7, s7, s11
	s_lshl_b32 s28, s69, 5
	s_ashr_i32 s29, s28, 31
	s_add_u32 s42, s6, s28
	s_addc_u32 s43, s7, s29
	s_lshl_b64 s[6:7], s[42:43], 11
	s_add_u32 s8, s65, s6
	s_addc_u32 s9, s70, s7
	s_lshl_b32 s6, s1, 6
	s_ashr_i32 s7, s6, 31
	v_bfe_u32 v180, v32, 5, 1
	s_lshl_b64 s[92:93], s[6:7], 1
	v_and_b32_e32 v179, 31, v32
	s_add_u32 s8, s8, s92
	v_lshlrev_b32_e32 v182, 4, v180
	s_addc_u32 s9, s9, s93
	v_lshl_or_b32 v0, v179, 11, v182
	s_cmp_lg_u32 s100, 0
	s_cbranch_scc1 .Lmy_pf_q
	global_load_dwordx4 v[114:117], v0, s[8:9]
	global_load_dwordx4 v[110:113], v0, s[8:9] offset:32
	global_load_dwordx4 v[106:109], v0, s[8:9] offset:64
	global_load_dwordx4 v[102:105], v0, s[8:9] offset:96
.Lmy_pf_q:
	s_lshl_b64 s[8:9], s[40:41], 15
	s_add_u32 s39, s4, s8
	s_addc_u32 s54, s5, s9
	s_lshl_b64 s[8:9], s[10:11], 2
	s_add_u32 s1, s39, s8
	s_addc_u32 s11, s54, s9
	s_lshl_b64 s[8:9], s[28:29], 2
	s_add_u32 s8, s1, s8
	s_addc_u32 s9, s11, s9
	v_lshlrev_b32_e32 v170, 2, v179
	s_cmp_lg_u32 s100, 0
	s_cbranch_scc1 .Lmy_pf_c
	global_load_dword v16, v170, s[8:9]
.Lmy_pf_c:
	s_cmp_lt_u32 s34, 64
	s_cselect_b64 s[8:9], -1, 0
	s_cmp_gt_u32 s34, 63
	v_and_b32_e32 v178, 63, v32
	s_cbranch_scc1 .LBB0_269
	s_lshl_b64 s[50:51], s[40:41], 9
	s_add_u32 s1, s35, s50
	s_addc_u32 s11, s80, s51
	s_add_i32 s50, s40, 0x80
	s_ashr_i32 s51, s50, 31
	s_lshl_b64 s[50:51], s[50:51], 9
	s_add_u32 s50, s35, s50
	s_addc_u32 s51, s80, s51
	v_lshlrev_b32_e32 v2, 3, v178
	s_cmp_lg_u32 s100, 0
	s_cbranch_scc1 .Lmy_pf_n
	global_load_dwordx2 v[12:13], v2, s[50:51]
.Lmy_pf_n:
	s_lshl_b32 s50, s99, 2
	v_lshl_or_b32 v0, s40, 6, v178
	s_ashr_i32 s51, s50, 31
	v_ashrrev_i32_e32 v1, 31, v0
	s_lshl_b64 s[50:51], s[50:51], 2
	v_lshl_add_u64 v[0:1], v[0:1], 2, s[26:27]
	s_add_u32 s50, s1, s50
	s_addc_u32 s51, s11, s51
	s_cmp_lg_u32 s100, 0
	s_cbranch_scc1 .Lmy_pf_t
	global_load_dword v14, v[0:1], off
	s_nop 0
	global_load_dwordx4 v[0:3], v101, s[50:51]
.Lmy_pf_t:
	s_branch .LBB0_270

.LBB0_270:
	v_mov_b32_e32 v5, s43
	v_or_b32_e32 v4, s42, v179
	v_lshlrev_b64 v[4:5], 11, v[4:5]
	v_lshlrev_b32_e32 v6, 3, v180
	v_lshl_add_u64 v[4:5], s[14:15], 0, v[4:5]
	v_lshl_add_u64 v[4:5], s[6:7], 1, v[4:5]
	v_lshlrev_b32_e32 v100, 1, v6
	v_lshl_add_u64 v[22:23], v[4:5], 0, v[100:101]
	s_cmp_lg_u32 s100, 0
	s_cbranch_scc1 .Lmy_pf_k
	global_load_dwordx4 v[134:137], v[22:23], off offset:96
	global_load_dwordx4 v[138:141], v[22:23], off offset:64
	global_load_dwordx4 v[142:145], v[22:23], off offset:32
	s_nop 0
	global_load_dwordx4 v[146:149], v[22:23], off
	s_waitcnt vmcnt(8)
	v_lshlrev_b32_e32 v15, 16, v114
	v_cmp_eq_u32_e64 s[6:7], 0, v178
	s_waitcnt vmcnt(0)
	s_branch .Lmy_pf_done
.Lmy_pf_k:
	v_mov_b32_e32 v16, v150
	s_cmp_gt_u32 s34, 63
	s_cbranch_scc1 .Lmy_pf_k2
	v_mov_b32_e32 v14, v151
	v_mov_b32_e32 v12, v152
	v_mov_b32_e32 v13, v153
	v_mov_b32_e32 v0, v154
	v_mov_b32_e32 v1, v155
	v_mov_b32_e32 v2, v156
	v_mov_b32_e32 v3, v157
.Lmy_pf_k2:
	v_lshlrev_b32_e32 v15, 16, v114
	v_cmp_eq_u32_e64 s[6:7], 0, v178
.Lmy_pf_done:
	s_nop 0
	v_lshlrev_b32_e32 v17, 16, v146
	v_fma_f32 v15, v15, v17, 0
	v_and_b32_e32 v17, 0xffff0000, v114
	v_and_b32_e32 v22, 0xffff0000, v146
	v_fmac_f32_e32 v15, v17, v22
	v_lshlrev_b32_e32 v17, 16, v115
	v_lshlrev_b32_e32 v22, 16, v147
	v_fmac_f32_e32 v15, v17, v22
	v_and_b32_e32 v17, 0xffff0000, v115
	v_and_b32_e32 v22, 0xffff0000, v147
	v_fmac_f32_e32 v15, v17, v22
	v_lshlrev_b32_e32 v17, 16, v116
	v_lshlrev_b32_e32 v22, 16, v148
	v_fmac_f32_e32 v15, v17, v22
	v_and_b32_e32 v17, 0xffff0000, v116
	v_and_b32_e32 v22, 0xffff0000, v148
	v_fmac_f32_e32 v15, v17, v22
	v_lshlrev_b32_e32 v17, 16, v117
	v_lshlrev_b32_e32 v22, 16, v149
	v_fmac_f32_e32 v15, v17, v22
	v_and_b32_e32 v17, 0xffff0000, v117
	v_and_b32_e32 v22, 0xffff0000, v149
	v_fmac_f32_e32 v15, v17, v22
	v_lshlrev_b32_e32 v17, 16, v110
	v_lshlrev_b32_e32 v22, 16, v142
	v_fmac_f32_e32 v15, v17, v22
	v_and_b32_e32 v17, 0xffff0000, v110
	v_and_b32_e32 v18, 0xffff0000, v142
	v_fmac_f32_e32 v15, v17, v18
	v_lshlrev_b32_e32 v17, 16, v111
	v_lshlrev_b32_e32 v18, 16, v143
	v_fmac_f32_e32 v15, v17, v18
	v_and_b32_e32 v17, 0xffff0000, v111
	v_and_b32_e32 v18, 0xffff0000, v143
	v_fmac_f32_e32 v15, v17, v18
	v_lshlrev_b32_e32 v17, 16, v112
	v_lshlrev_b32_e32 v18, 16, v144
	v_fmac_f32_e32 v15, v17, v18
	v_and_b32_e32 v17, 0xffff0000, v112
	v_and_b32_e32 v18, 0xffff0000, v144
	v_fmac_f32_e32 v15, v17, v18
	v_lshlrev_b32_e32 v17, 16, v113
	v_lshlrev_b32_e32 v18, 16, v145
	v_fmac_f32_e32 v15, v17, v18
	v_and_b32_e32 v17, 0xffff0000, v113
	v_and_b32_e32 v18, 0xffff0000, v145
	v_fmac_f32_e32 v15, v17, v18
	v_lshlrev_b32_e32 v17, 16, v106
	v_lshlrev_b32_e32 v18, 16, v138
	v_fmac_f32_e32 v15, v17, v18
	v_and_b32_e32 v17, 0xffff0000, v106
	v_and_b32_e32 v8, 0xffff0000, v138
	v_fmac_f32_e32 v15, v17, v8
	v_lshlrev_b32_e32 v8, 16, v107
	v_lshlrev_b32_e32 v17, 16, v139
	v_fmac_f32_e32 v15, v8, v17
	v_and_b32_e32 v8, 0xffff0000, v107
	v_and_b32_e32 v9, 0xffff0000, v139
	v_fmac_f32_e32 v15, v8, v9
	v_lshlrev_b32_e32 v8, 16, v108
	v_lshlrev_b32_e32 v9, 16, v140
	v_fmac_f32_e32 v15, v8, v9
	v_and_b32_e32 v8, 0xffff0000, v108
	v_and_b32_e32 v9, 0xffff0000, v140
	v_fmac_f32_e32 v15, v8, v9
	v_lshlrev_b32_e32 v8, 16, v109
	v_lshlrev_b32_e32 v9, 16, v141
	v_fmac_f32_e32 v15, v8, v9
	v_and_b32_e32 v8, 0xffff0000, v109
	v_and_b32_e32 v9, 0xffff0000, v141
	v_fmac_f32_e32 v15, v8, v9
	v_lshlrev_b32_e32 v8, 16, v102
	v_lshlrev_b32_e32 v9, 16, v134
	v_fmac_f32_e32 v15, v8, v9
	v_and_b32_e32 v8, 0xffff0000, v102
	v_and_b32_e32 v4, 0xffff0000, v134
	v_fmac_f32_e32 v15, v8, v4
	v_lshlrev_b32_e32 v4, 16, v103
	v_lshlrev_b32_e32 v8, 16, v135
	v_fmac_f32_e32 v15, v4, v8
	v_and_b32_e32 v4, 0xffff0000, v103
	v_and_b32_e32 v5, 0xffff0000, v135
	v_fmac_f32_e32 v15, v4, v5
	v_lshlrev_b32_e32 v4, 16, v104
	v_lshlrev_b32_e32 v5, 16, v136
	v_fmac_f32_e32 v15, v4, v5
	v_and_b32_e32 v4, 0xffff0000, v104
	v_and_b32_e32 v5, 0xffff0000, v136
	v_fmac_f32_e32 v15, v4, v5
	v_lshlrev_b32_e32 v4, 16, v105
	v_lshlrev_b32_e32 v5, 16, v137
	v_fmac_f32_e32 v15, v4, v5
	v_and_b32_e32 v4, 0xffff0000, v105
	v_and_b32_e32 v5, 0xffff0000, v137
	v_fmac_f32_e32 v15, v4, v5
	v_mov_b32_e32 v4, v15
	s_nop 1
	v_permlane32_swap_b32_e32 v15, v4
	v_add_f32_e32 v4, v15, v4
	ds_swizzle_b32 v5, v4 offset:swizzle(SWAP,16)
	s_waitcnt lgkmcnt(0)
	v_max_f32_e32 v5, v5, v5
	v_min_f32_e32 v4, v4, v5
	ds_swizzle_b32 v5, v4 offset:swizzle(SWAP,8)
	s_waitcnt lgkmcnt(0)
	v_max_f32_e32 v5, v5, v5
	v_min_f32_e32 v4, v4, v5
	ds_swizzle_b32 v5, v4 offset:swizzle(SWAP,4)
	s_waitcnt lgkmcnt(0)
	v_max_f32_e32 v5, v5, v5
	v_min_f32_e32 v4, v4, v5
	ds_swizzle_b32 v5, v4 offset:swizzle(SWAP,2)
	s_waitcnt lgkmcnt(0)
	v_max_f32_e32 v5, v5, v5
	v_min_f32_e32 v4, v4, v5
	ds_swizzle_b32 v5, v4 offset:swizzle(SWAP,1)
	s_and_saveexec_b64 s[50:51], s[6:7]
	s_cbranch_execz .LBB0_272
	s_lshl_b32 s1, s69, 2
	s_add_i32 s1, s1, 0
	s_add_i32 s1, s1, 0x1c908
	s_waitcnt lgkmcnt(0)
	v_max_f32_e32 v5, v5, v5
	v_max_f32_e32 v4, v4, v4
	v_min_f32_e32 v4, v4, v5
	v_mov_b32_e32 v5, s1
	ds_write_b32 v5, v4

.Lmy_fox_noq:
	s_or_b64 exec, exec, s[16:17]
	v_readlane_b32 s16, v241, 30
	v_readlane_b32 s17, v241, 31
	v_readlane_b32 s18, v241, 32
	v_readlane_b32 s19, v241, 33
	v_readlane_b32 s20, v241, 34
	v_readlane_b32 s21, v241, 35
	s_ashr_i32 s85, s84, 31
	s_sub_i32 s78, s47, s50
	s_lshl_b64 s[6:7], s[84:85], 2
	s_add_u32 s10, s39, s6
	s_addc_u32 s11, s54, s7
	s_lshl_b32 s33, s78, 4
	v_cmp_gt_i32_e64 s[8:9], s33, v19
	v_cmp_gt_i32_e64 s[6:7], s33, v18
	v_add_u32_e32 v17, 0x600, v181
	v_cndmask_b32_e64 v2, v181, v19, s[8:9]
	v_lshlrev_b32_e32 v2, 2, v2
	v_ashrrev_i32_e32 v3, 31, v2
	v_lshl_add_u64 v[8:9], v[2:3], 2, s[10:11]
	v_cndmask_b32_e64 v2, v181, v18, s[6:7]
	v_lshlrev_b32_e32 v2, 2, v2
	v_ashrrev_i32_e32 v3, 31, v2
	v_cmp_gt_i32_e32 vcc, s33, v17
	v_lshl_add_u64 v[4:5], v[2:3], 2, s[10:11]
	v_lshlrev_b32_e32 v0, 2, v181
	v_cndmask_b32_e32 v2, v181, v17, vcc
	v_lshlrev_b32_e32 v2, 2, v2
	v_ashrrev_i32_e32 v1, 31, v0
	v_ashrrev_i32_e32 v3, 31, v2
	v_lshl_add_u64 v[0:1], v[0:1], 2, s[10:11]
	v_lshl_add_u64 v[2:3], v[2:3], 2, s[10:11]
	global_load_dwordx4 v[12:15], v[0:1], off
	s_nop 0
	global_load_dwordx4 v[0:3], v[2:3], off
	s_nop 0
	global_load_dwordx4 v[4:7], v[4:5], off
	s_nop 0
	global_load_dwordx4 v[8:11], v[8:9], off
	s_lshl_b32 s1, s1, 2
	s_add_i32 s29, s1, 0
	v_lshlrev_b32_e32 v33, 4, v181
	s_add_i32 s29, s29, 0x1c800
	v_cmp_gt_i32_e64 s[10:11], s33, v181
	s_waitcnt vmcnt(0)
	s_cmp_lg_u32 s34, 0
	s_cbranch_scc1 .Lmy_fox_nopub
	v_readfirstlane_b32 s100, v201
	v_mov_b32_e32 v21, 0x1c9f0
	v_mov_b32_e32 v20, s100
	ds_write_b32 v21, v20
.Lmy_fox_nopub:
	s_and_saveexec_b64 s[60:61], s[10:11]
	s_cbranch_execz .LBB0_280
	v_ashrrev_i32_e32 v20, 5, v181
	v_lshl_add_u32 v20, v20, 2, s29
	ds_read_b32 v20, v20
	s_waitcnt lgkmcnt(0)
	v_add_f32_e32 v12, v12, v20
	v_mul_f32_e32 v12, 0xbfb8aa3b, v12
	v_cvt_pk_bf16_f32 v21, v12, 0
	v_lshlrev_b32_e32 v21, 16, v21
	v_add_f32_e32 v13, v13, v20
	v_sub_f32_e32 v21, v12, v21
	v_mul_f32_e32 v13, 0xbfb8aa3b, v13
	v_add_f32_e32 v15, v15, v20
	v_cvt_pk_bf16_f32 v12, v12, v21
	v_cvt_pk_bf16_f32 v21, v13, 0
	v_mul_f32_e32 v15, 0xbfb8aa3b, v15
	v_lshlrev_b32_e32 v21, 16, v21
	v_add_f32_e32 v14, v14, v20
	v_cvt_pk_bf16_f32 v20, v15, 0
	v_sub_f32_e32 v21, v13, v21
	v_mul_f32_e32 v14, 0xbfb8aa3b, v14
	v_lshlrev_b32_e32 v20, 16, v20
	v_cvt_pk_bf16_f32 v13, v13, v21
	v_cvt_pk_bf16_f32 v21, v14, 0
	v_sub_f32_e32 v20, v15, v20
	v_lshlrev_b32_e32 v21, 16, v21
	v_cvt_pk_bf16_f32 v15, v15, v20
	v_add_u32_e32 v20, 0, v33
	v_sub_f32_e32 v21, v14, v21
	v_add_u32_e32 v20, 0x14800, v20
	v_cvt_pk_bf16_f32 v14, v14, v21
	ds_write_b128 v20, v[12:15]
	s_or_b64 exec, exec, s[60:61]
	s_and_saveexec_b64 s[10:11], s[8:9]
	s_cbranch_execnz .LBB0_281

.LBB0_307:
	s_cmp_lg_u32 0, -1
	s_cselect_b32 s1, 0, 0
	s_addk_i32 s1, 0x6000
	v_add3_u32 v64, v185, s1, v183
	v_cvt_pk_bf16_f32 v68, v48, v49
	v_cvt_pk_bf16_f32 v69, v50, v51
	v_cvt_pk_bf16_f32 v70, v52, v53
	v_cvt_pk_bf16_f32 v71, v54, v55
	v_cvt_pk_bf16_f32 v72, v56, v57
	v_cvt_pk_bf16_f32 v73, v58, v59
	v_cvt_pk_bf16_f32 v74, v60, v61
	v_cvt_pk_bf16_f32 v75, v62, v63
	v_cvt_pk_bf16_f32 v76, v32, v33
	v_cvt_pk_bf16_f32 v77, v34, v35
	v_cvt_pk_bf16_f32 v78, v36, v37
	v_cvt_pk_bf16_f32 v79, v38, v39
	v_cvt_pk_bf16_f32 v80, v40, v41
	v_cvt_pk_bf16_f32 v81, v42, v43
	v_cvt_pk_bf16_f32 v82, v44, v45
	v_cvt_pk_bf16_f32 v83, v46, v47
	v_add3_u32 v64, v64, v186, s34
	ds_read_b64_tr_b16 v[84:85],v64 offset:0
	ds_read_b64_tr_b16 v[86:87],v64 offset:512
	ds_read_b64_tr_b16 v[88:89],v64 offset:1024
	ds_read_b64_tr_b16 v[90:91],v64 offset:1536
	ds_read_b64_tr_b16 v[92:93],v64 offset:2048
	ds_read_b64_tr_b16 v[94:95],v64 offset:2560
	ds_read_b64_tr_b16 v[96:97],v64 offset:3072
	ds_read_b64_tr_b16 v[98:99],v64 offset:3584
	s_waitcnt lgkmcnt(0)
	s_nop 0
	v_mfma_f32_32x32x16_bf16 v[0:15], v[68:71], v[84:87], v[0:15]
	ds_read_b64_tr_b16 v[84:85],v64 offset:4096
	ds_read_b64_tr_b16 v[86:87],v64 offset:4608
	v_mfma_f32_32x32x16_bf16 v[0:15], v[72:75], v[88:91], v[0:15]
	ds_read_b64_tr_b16 v[88:89],v64 offset:5120
	ds_read_b64_tr_b16 v[90:91],v64 offset:5632
	v_mfma_f32_32x32x16_bf16 v[0:15], v[76:79], v[92:95], v[0:15]
	ds_read_b64_tr_b16 v[92:93],v64 offset:6144
	ds_read_b64_tr_b16 v[94:95],v64 offset:6656
	v_mfma_f32_32x32x16_bf16 v[0:15], v[80:83], v[96:99], v[0:15]
	ds_read_b64_tr_b16 v[96:97],v64 offset:7168
	ds_read_b64_tr_b16 v[98:99],v64 offset:7680
	s_waitcnt lgkmcnt(0)
	v_mfma_f32_32x32x16_bf16 v[16:31], v[68:71], v[84:87], v[16:31]
	v_cmp_eq_u32_e32 vcc, 0, v181
	v_mov_b32_e32 v64, 0
	v_mfma_f32_32x32x16_bf16 v[16:31], v[72:75], v[88:91], v[16:31]
	v_mfma_f32_32x32x16_bf16 v[16:31], v[76:79], v[92:95], v[16:31]
	v_mfma_f32_32x32x16_bf16 v[16:31], v[80:83], v[96:99], v[16:31]
	v_mov_b32_e32 v64, v201
	v_mov_b32_e32 v246, 0x1c9f0
	ds_read_b32 v246, v246
	v_writelane_b32 v241, s16, 30
	v_writelane_b32 v241, s17, 31
	v_writelane_b32 v241, s18, 32
	v_writelane_b32 v241, s19, 33
	v_writelane_b32 v241, s20, 34
	v_writelane_b32 v241, s21, 35
	s_waitcnt lgkmcnt(0)
	v_readfirstlane_b32 s100, v246
	s_mov_b32 s101, -1
	s_cmpk_lt_u32 s100, 0x200
	s_cbranch_scc0 .Lmy_fox_nopf
	s_add_i32 s100, s100, s98
	s_lshr_b32 s16, s100, 5
	s_and_b32 s16, s16, 0x7fffff0
	s_bfe_u32 s17, s100, 0x40003
	s_or_b32 s16, s16, s17
	s_lshr_b32 s17, s100, 4
	s_and_b32 s17, s17, 24
	s_xor_b32 s17, s17, 31
	s_and_b32 s18, s100, 7
	s_sub_i32 s17, s17, s18
	s_mov_b32 s101, s100
	v_readfirstlane_b32 s100, v181
	s_lshr_b32 s18, s16, 4
	s_lshl_b32 s18, s18, 13
	s_lshl_b32 s19, s17, 8
	s_add_i32 s18, s18, s19
	s_lshr_b32 s19, s100, 1
	s_add_i32 s18, s18, s19
	s_lshl_b32 s18, s18, 11
	s_and_b32 s19, s16, 15
	s_lshl_b32 s19, s19, 7
	s_add_i32 s18, s18, s19
	s_add_u32 s20, s65, s18
	s_addc_u32 s21, s70, 0
	v_lshlrev_b32_e32 v246, 11, v179
	v_lshl_or_b32 v246, v180, 4, v246
	global_load_dwordx4 v[114:117], v246, s[20:21]
	global_load_dwordx4 v[110:113], v246, s[20:21] offset:32
	global_load_dwordx4 v[106:109], v246, s[20:21] offset:64
	global_load_dwordx4 v[102:105], v246, s[20:21] offset:96
	s_add_u32 s20, s14, s18
	s_addc_u32 s21, s15, 0
	global_load_dwordx4 v[134:137], v246, s[20:21] offset:96
	global_load_dwordx4 v[138:141], v246, s[20:21] offset:64
	global_load_dwordx4 v[142:145], v246, s[20:21] offset:32
	global_load_dwordx4 v[146:149], v246, s[20:21]
	s_lshl_b32 s18, s16, 15
	s_lshl_b32 s19, s17, 10
	s_add_i32 s18, s18, s19
	s_lshl_b32 s19, s100, 1
	s_add_i32 s18, s18, s19
	s_add_u32 s20, s4, s18
	s_addc_u32 s21, s5, 0
	v_lshlrev_b32_e32 v247, 2, v179
	global_load_dword v150, v247, s[20:21]
	s_cmp_lg_u32 s100, 0
	s_cbranch_scc1 .Lmy_fox_nopf
	v_lshl_or_b32 v247, s16, 6, v178
	v_lshlrev_b32_e32 v247, 2, v247
	global_load_dword v151, v247, s[26:27]
	s_add_i32 s18, s16, 0x80
	s_lshl_b32 s18, s18, 9
	s_add_u32 s20, s35, s18
	s_addc_u32 s21, s80, 0
	v_lshlrev_b32_e32 v247, 3, v178
	global_load_dwordx2 v[152:153], v247, s[20:21]
	s_lshl_b32 s18, s16, 9
	s_lshl_b32 s19, s17, 4
	s_add_i32 s18, s18, s19
	s_add_u32 s20, s35, s18
	s_addc_u32 s21, s80, 0
	global_load_dwordx4 v[154:157], v101, s[20:21]
.Lmy_fox_nopf:
	v_writelane_b32 v241, s101, 36
	v_readlane_b32 s16, v241, 30
	v_readlane_b32 s17, v241, 31
	v_readlane_b32 s18, v241, 32
	v_readlane_b32 s19, v241, 33
	v_readlane_b32 s20, v241, 34
	v_readlane_b32 s21, v241, 35
	s_add_u32 s100, s12, s92
	s_addc_u32 s101, s13, s93
	v_ashrrev_i32_e32 v244, 3, v178
	v_mov_b32_e32 v245, 0
	v_lshl_add_u64 v[244:245], s[42:43], 0, v[244:245]
	v_lshlrev_b64 v[244:245], 11, v[244:245]
	v_lshlrev_b32_e32 v246, 4, v178
	v_and_b32_e32 v246, 0x70, v246
	v_mov_b32_e32 v247, 0
	v_lshl_add_u64 v[246:247], s[100:101], 0, v[246:247]
	v_lshl_add_u64 v[244:245], v[246:247], 0, v[244:245]
	s_mov_b32 s100, 0x4000
	s_mov_b32 s101, 0
	global_load_dwordx4 v[208:211], v[244:245], off
	v_lshl_add_u64 v[244:245], v[244:245], 0, s[100:101]
	global_load_dwordx4 v[226:229], v[244:245], off
	v_lshl_add_u64 v[244:245], v[244:245], 0, s[100:101]
	global_load_dwordx4 v[230:233], v[244:245], off
	v_lshl_add_u64 v[244:245], v[244:245], 0, s[100:101]
	global_load_dwordx4 v[234:237], v[244:245], off
	v_add_f32_e32 v48, v48, v49
	v_add_f32_e32 v48, v50, v48
	v_add_f32_e32 v48, v51, v48
	v_add_f32_e32 v48, v52, v48
	v_add_f32_e32 v48, v53, v48
	v_add_f32_e32 v48, v54, v48
	v_add_f32_e32 v48, v55, v48
	v_add_f32_e32 v48, v56, v48
	v_add_f32_e32 v48, v57, v48
	v_add_f32_e32 v48, v58, v48
	v_add_f32_e32 v48, v59, v48
	v_add_f32_e32 v48, v60, v48
	v_add_f32_e32 v48, v61, v48
	v_add_f32_e32 v48, v62, v48
	v_add_f32_e32 v48, v63, v48
	v_add_f32_e32 v32, v32, v48
	v_add_f32_e32 v32, v33, v32
	v_add_f32_e32 v32, v34, v32
	v_add_f32_e32 v32, v35, v32
	v_add_f32_e32 v32, v36, v32
	v_add_f32_e32 v32, v37, v32
	v_add_f32_e32 v32, v38, v32
	v_add_f32_e32 v32, v39, v32
	v_add_f32_e32 v32, v40, v32
	v_add_f32_e32 v32, v41, v32
	v_add_f32_e32 v32, v42, v32
	v_add_f32_e32 v32, v43, v32
	v_add_f32_e32 v32, v44, v32
	v_add_f32_e32 v32, v45, v32
	v_add_f32_e32 v32, v46, v32
	v_add_f32_e32 v32, v47, v32
	v_add_f32_e32 v32, v65, v32
	v_mov_b32_e32 v33, v32
	s_nop 1
	v_permlane32_swap_b32_e32 v32, v33
	s_and_saveexec_b64 s[8:9], s[6:7]
	v_lshl_add_u32 v34, v179, 2, s41
	v_add_f32_e32 v32, v32, v33
	ds_write_b32 v34, v32 offset:49280
	s_or_b64 exec, exec, s[8:9]
	s_waitcnt lgkmcnt(0)
	ds_read_b128 v[32:35], v66 offset:49280
	ds_read_b128 v[36:39], v66 offset:49312
	s_lshl_b64 s[6:7], s[10:11], 1
	s_add_u32 s1, s73, s6
	s_addc_u32 s7, s64, s7
	s_waitcnt lgkmcnt(1)
	v_rcp_f32_e32 v40, v32
	s_lshl_b32 s6, s69, 12
	v_rcp_f32_e32 v41, v33
	s_add_i32 s8, s6, 0
	v_lshlrev_b32_e32 v48, 1, v179
	v_lshlrev_b32_e32 v49, 9, v180
	v_mul_f32_e32 v0, v0, v40
	v_add3_u32 v48, s8, v48, v49
	v_cvt_pk_bf16_f32 v0, v0, s0
	v_rcp_f32_e32 v42, v34
	v_rcp_f32_e32 v43, v35
	s_waitcnt lgkmcnt(0)
	v_rcp_f32_e32 v44, v36
	ds_read_b128 v[32:35], v66 offset:49344
	v_rcp_f32_e32 v45, v37
	v_rcp_f32_e32 v46, v38
	v_rcp_f32_e32 v47, v39
	ds_read_b128 v[36:39], v66 offset:49376
	ds_write_b16 v48, v0 offset:51200
	v_mul_f32_e32 v0, v16, v40
	v_cvt_pk_bf16_f32 v0, v0, s0
	ds_write_b16 v48, v0 offset:51264
	v_mul_f32_e32 v0, v1, v41
	v_cvt_pk_bf16_f32 v0, v0, s0
	ds_write_b16 v48, v0 offset:51328
	v_mul_f32_e32 v0, v17, v41
	v_cvt_pk_bf16_f32 v0, v0, s0
	ds_write_b16 v48, v0 offset:51392
	v_mul_f32_e32 v0, v2, v42
	v_cvt_pk_bf16_f32 v0, v0, s0
	ds_write_b16 v48, v0 offset:51456
	v_mul_f32_e32 v0, v18, v42
	v_cvt_pk_bf16_f32 v0, v0, s0
	ds_write_b16 v48, v0 offset:51520
	v_mul_f32_e32 v0, v3, v43
	v_cvt_pk_bf16_f32 v0, v0, s0
	ds_write_b16 v48, v0 offset:51584
	v_mul_f32_e32 v0, v19, v43
	v_cvt_pk_bf16_f32 v0, v0, s0
	ds_write_b16 v48, v0 offset:51648
	v_mul_f32_e32 v0, v4, v44
	v_cvt_pk_bf16_f32 v0, v0, s0
	ds_write_b16 v48, v0 offset:52224
	v_mul_f32_e32 v0, v20, v44
	v_cvt_pk_bf16_f32 v0, v0, s0
	ds_write_b16 v48, v0 offset:52288
	v_mul_f32_e32 v0, v5, v45
	v_cvt_pk_bf16_f32 v0, v0, s0
	ds_write_b16 v48, v0 offset:52352
	v_mul_f32_e32 v0, v21, v45
	v_cvt_pk_bf16_f32 v0, v0, s0
	ds_write_b16 v48, v0 offset:52416
	v_mul_f32_e32 v0, v6, v46
	v_cvt_pk_bf16_f32 v0, v0, s0
	ds_write_b16 v48, v0 offset:52480
	v_mul_f32_e32 v0, v22, v46
	v_cvt_pk_bf16_f32 v0, v0, s0
	s_waitcnt lgkmcnt(14)
	v_rcp_f32_e32 v32, v32
	ds_write_b16 v48, v0 offset:52544
	v_mul_f32_e32 v0, v7, v47
	v_cvt_pk_bf16_f32 v0, v0, s0
	ds_write_b16 v48, v0 offset:52608
	v_mul_f32_e32 v0, v23, v47
	v_cvt_pk_bf16_f32 v0, v0, s0
	v_rcp_f32_e32 v33, v33
	ds_write_b16 v48, v0 offset:52672
	v_mul_f32_e32 v0, v8, v32
	v_cvt_pk_bf16_f32 v0, v0, s0
	ds_write_b16 v48, v0 offset:53248
	v_mul_f32_e32 v0, v24, v32
	v_cvt_pk_bf16_f32 v0, v0, s0
	v_rcp_f32_e32 v34, v34
	ds_write_b16 v48, v0 offset:53312
	v_mul_f32_e32 v0, v9, v33
	v_cvt_pk_bf16_f32 v0, v0, s0
	ds_write_b16 v48, v0 offset:53376
	v_mul_f32_e32 v0, v25, v33
	v_cvt_pk_bf16_f32 v0, v0, s0
	v_rcp_f32_e32 v35, v35
	ds_write_b16 v48, v0 offset:53440
	v_mul_f32_e32 v0, v10, v34
	v_cvt_pk_bf16_f32 v0, v0, s0
	ds_write_b16 v48, v0 offset:53504
	v_mul_f32_e32 v0, v26, v34
	v_cvt_pk_bf16_f32 v0, v0, s0
	s_waitcnt lgkmcnt(14)
	v_rcp_f32_e32 v36, v36
	ds_write_b16 v48, v0 offset:53568
	v_mul_f32_e32 v0, v11, v35
	v_cvt_pk_bf16_f32 v0, v0, s0
	ds_write_b16 v48, v0 offset:53632
	v_mul_f32_e32 v0, v27, v35
	v_cvt_pk_bf16_f32 v0, v0, s0
	v_rcp_f32_e32 v37, v37
	ds_write_b16 v48, v0 offset:53696
	v_mul_f32_e32 v0, v12, v36
	v_cvt_pk_bf16_f32 v0, v0, s0
	ds_write_b16 v48, v0 offset:54272
	v_mul_f32_e32 v0, v28, v36
	v_cvt_pk_bf16_f32 v0, v0, s0
	v_rcp_f32_e32 v38, v38
	ds_write_b16 v48, v0 offset:54336
	v_mul_f32_e32 v0, v13, v37
	v_cvt_pk_bf16_f32 v0, v0, s0
	ds_write_b16 v48, v0 offset:54400
	v_mul_f32_e32 v0, v29, v37
	v_cvt_pk_bf16_f32 v0, v0, s0
	v_rcp_f32_e32 v39, v39
	ds_write_b16 v48, v0 offset:54464
	v_mul_f32_e32 v0, v14, v38
	v_cvt_pk_bf16_f32 v0, v0, s0
	ds_write_b16 v48, v0 offset:54528
	v_mul_f32_e32 v0, v30, v38
	v_cvt_pk_bf16_f32 v0, v0, s0
	ds_write_b16 v48, v0 offset:54592
	v_mul_f32_e32 v0, v15, v39
	v_cvt_pk_bf16_f32 v0, v0, s0
	ds_write_b16 v48, v0 offset:54656
	v_mul_f32_e32 v0, v31, v39
	v_cvt_pk_bf16_f32 v0, v0, s0
	ds_write_b16 v48, v0 offset:54720
	s_add_u32 s6, s1, s92
	s_addc_u32 s7, s7, s93
	s_waitcnt lgkmcnt(0)
	s_add_u32 s10, s12, s92
	v_ashrrev_i32_e32 v2, 3, v178
	v_lshlrev_b32_e32 v0, 4, v178
	v_ashrrev_i32_e32 v3, 31, v2
	v_and_b32_e32 v100, 0x70, v0
	s_addc_u32 s11, s13, s93
	v_lshl_add_u64 v[0:1], s[42:43], 0, v[2:3]
	v_lshl_add_u64 v[4:5], s[10:11], 0, v[100:101]
	v_lshlrev_b64 v[0:1], 11, v[0:1]
	v_lshl_add_u64 v[0:1], v[4:5], 0, v[0:1]
	s_waitcnt vmcnt(0)
	v_mov_b32_e32 v8, v208
	v_mov_b32_e32 v9, v209
	v_mov_b32_e32 v10, v210
	v_mov_b32_e32 v11, v211
	v_add_u32_e32 v6, 8, v2
	v_ashrrev_i32_e32 v7, 31, v6
	v_lshl_add_u64 v[0:1], s[42:43], 0, v[6:7]
	v_lshlrev_b64 v[0:1], 11, v[0:1]
	v_lshl_add_u64 v[0:1], v[4:5], 0, v[0:1]
	v_mov_b32_e32 v12, v226
	v_mov_b32_e32 v13, v227
	v_mov_b32_e32 v14, v228
	v_mov_b32_e32 v15, v229
	v_add_u32_e32 v32, s8, v100
	v_lshl_add_u32 v0, v2, 7, v32
	ds_read_b128 v[16:19], v0 offset:51200
	s_waitcnt lgkmcnt(0)
	v_lshlrev_b32_e32 v24, 16, v16
	v_and_b32_e32 v25, 0xffff0000, v16
	s_waitcnt vmcnt(1)
	v_lshlrev_b32_e32 v20, 16, v8
	v_and_b32_e32 v21, 0xffff0000, v8
	v_mul_f32_e32 v1, 0xbfb8aa3b, v20
	v_exp_f32_e32 v1, v1
	v_mul_f32_e32 v8, 0xbfb8aa3b, v21
	v_exp_f32_e32 v8, v8
	s_waitcnt vmcnt(0)
	v_lshlrev_b32_e32 v28, 16, v12
	v_add_f32_e32 v0, 1.0, v1
	v_rcp_f32_e32 v22, v0
	v_add_f32_e32 v0, 1.0, v8
	v_rcp_f32_e32 v23, v0
	v_lshl_add_u64 v[0:1], s[6:7], 0, v[100:101]
	v_and_b32_e32 v29, 0xffff0000, v12
	v_mul_f32_e32 v12, 0xbfb8aa3b, v28
	v_pk_mul_f32 v[20:21], v[22:23], v[20:21]
	v_lshlrev_b32_e32 v22, 16, v9
	v_and_b32_e32 v23, 0xffff0000, v9
	v_mul_f32_e32 v8, 0xbfb8aa3b, v22
	v_exp_f32_e32 v16, v8
	v_mul_f32_e32 v8, 0xbfb8aa3b, v23
	v_exp_f32_e32 v26, v8
	v_pk_mul_f32 v[8:9], v[20:21], v[24:25]
	v_add_f32_e32 v16, 1.0, v16
	v_rcp_f32_e32 v20, v16
	v_add_f32_e32 v16, 1.0, v26
	v_rcp_f32_e32 v21, v16
	v_cvt_pk_bf16_f32 v8, v8, v9
	v_lshlrev_b32_e32 v16, 16, v17
	v_and_b32_e32 v17, 0xffff0000, v17
	v_pk_mul_f32 v[20:21], v[20:21], v[22:23]
	v_lshlrev_b32_e32 v22, 16, v10
	v_and_b32_e32 v23, 0xffff0000, v10
	v_mul_f32_e32 v9, 0xbfb8aa3b, v22
	v_exp_f32_e32 v9, v9
	v_mul_f32_e32 v10, 0xbfb8aa3b, v23
	v_exp_f32_e32 v10, v10
	v_pk_mul_f32 v[16:17], v[20:21], v[16:17]
	v_add_f32_e32 v9, 1.0, v9
	v_rcp_f32_e32 v20, v9
	v_add_f32_e32 v9, 1.0, v10
	v_rcp_f32_e32 v21, v9
	v_add_u32_e32 v26, 16, v2
	v_cvt_pk_bf16_f32 v9, v16, v17
	v_lshlrev_b32_e32 v16, 16, v18
	v_and_b32_e32 v17, 0xffff0000, v18
	v_pk_mul_f32 v[20:21], v[20:21], v[22:23]
	v_ashrrev_i32_e32 v27, 31, v26
	v_pk_mul_f32 v[16:17], v[20:21], v[16:17]
	v_lshlrev_b32_e32 v24, 16, v11
	v_lshl_add_u64 v[20:21], s[42:43], 0, v[26:27]
	v_and_b32_e32 v25, 0xffff0000, v11
	v_mul_f32_e32 v10, 0xbfb8aa3b, v24
	v_lshlrev_b64 v[20:21], 11, v[20:21]
	v_exp_f32_e32 v11, v10
	v_mul_f32_e32 v10, 0xbfb8aa3b, v25
	v_lshl_add_u64 v[20:21], v[4:5], 0, v[20:21]
	v_exp_f32_e32 v18, v10
	v_mov_b32_e32 v20, v230
	v_mov_b32_e32 v21, v231
	v_mov_b32_e32 v22, v232
	v_mov_b32_e32 v23, v233
	v_add_f32_e32 v11, 1.0, v11
	v_cvt_pk_bf16_f32 v10, v16, v17
	v_rcp_f32_e32 v16, v11
	v_add_f32_e32 v11, 1.0, v18
	v_rcp_f32_e32 v17, v11
	v_lshlrev_b32_e32 v18, 16, v19
	v_and_b32_e32 v19, 0xffff0000, v19
	v_exp_f32_e32 v12, v12
	v_pk_mul_f32 v[16:17], v[16:17], v[24:25]
	s_nop 0
	v_pk_mul_f32 v[16:17], v[16:17], v[18:19]
	s_nop 0
	v_cvt_pk_bf16_f32 v11, v16, v17
	v_lshlrev_b64 v[16:17], 11, v[2:3]
	v_lshl_add_u64 v[24:25], v[0:1], 0, v[16:17]
	v_mul_f32_e32 v16, 0xbfb8aa3b, v29
	v_lshl_add_u32 v3, v6, 7, v32
	v_exp_f32_e32 v31, v16
	ds_read_b128 v[16:19], v3 offset:51200
	v_add_f32_e32 v3, 1.0, v12
	v_rcp_f32_e32 v30, v3
	v_add_f32_e32 v3, 1.0, v31
	v_lshlrev_b32_e32 v12, 16, v13
	v_rcp_f32_e32 v31, v3
	v_and_b32_e32 v13, 0xffff0000, v13
	v_mul_f32_e32 v3, 0xbfb8aa3b, v12
	global_store_dwordx4 v[24:25], v[8:11], off
	v_exp_f32_e32 v3, v3
	v_lshlrev_b64 v[6:7], 11, v[6:7]
	s_waitcnt lgkmcnt(0)
	v_lshlrev_b32_e32 v8, 16, v16
	v_and_b32_e32 v9, 0xffff0000, v16
	v_mul_f32_e32 v16, 0xbfb8aa3b, v13
	v_exp_f32_e32 v16, v16
	v_pk_mul_f32 v[10:11], v[30:31], v[28:29]
	v_add_f32_e32 v3, 1.0, v3
	v_pk_mul_f32 v[8:9], v[10:11], v[8:9]
	v_rcp_f32_e32 v10, v3
	v_add_f32_e32 v3, 1.0, v16
	v_rcp_f32_e32 v11, v3
	v_cvt_pk_bf16_f32 v8, v8, v9
	v_lshlrev_b32_e32 v16, 16, v17
	v_and_b32_e32 v17, 0xffff0000, v17
	v_pk_mul_f32 v[10:11], v[10:11], v[12:13]
	v_lshlrev_b32_e32 v12, 16, v14
	v_and_b32_e32 v13, 0xffff0000, v14
	v_mul_f32_e32 v3, 0xbfb8aa3b, v12
	v_exp_f32_e32 v3, v3
	v_mul_f32_e32 v9, 0xbfb8aa3b, v13
	v_exp_f32_e32 v9, v9
	v_pk_mul_f32 v[10:11], v[10:11], v[16:17]
	v_add_f32_e32 v3, 1.0, v3
	v_rcp_f32_e32 v16, v3
	v_add_f32_e32 v3, 1.0, v9
	v_rcp_f32_e32 v17, v3
	v_lshlrev_b32_e32 v14, 16, v15
	v_and_b32_e32 v15, 0xffff0000, v15
	v_mul_f32_e32 v3, 0xbfb8aa3b, v14
	v_pk_mul_f32 v[12:13], v[16:17], v[12:13]
	v_add_u32_e32 v16, 24, v2
	v_cvt_pk_bf16_f32 v9, v10, v11
	v_lshlrev_b32_e32 v10, 16, v18
	v_and_b32_e32 v11, 0xffff0000, v18
	v_exp_f32_e32 v18, v3
	v_mul_f32_e32 v3, 0xbfb8aa3b, v15
	v_ashrrev_i32_e32 v17, 31, v16
	v_exp_f32_e32 v24, v3
	v_lshl_add_u64 v[2:3], s[42:43], 0, v[16:17]
	v_lshlrev_b64 v[2:3], 11, v[2:3]
	v_lshl_add_u64 v[2:3], v[4:5], 0, v[2:3]
	v_mov_b32_e32 v2, v234
	v_mov_b32_e32 v3, v235
	v_mov_b32_e32 v4, v236
	v_mov_b32_e32 v5, v237
	v_pk_mul_f32 v[10:11], v[12:13], v[10:11]
	v_add_f32_e32 v12, 1.0, v18
	v_add_f32_e32 v13, 1.0, v24
	v_rcp_f32_e32 v12, v12
	v_rcp_f32_e32 v13, v13
	v_lshlrev_b32_e32 v18, 16, v19
	v_and_b32_e32 v19, 0xffff0000, v19
	v_cvt_pk_bf16_f32 v10, v10, v11
	v_pk_mul_f32 v[12:13], v[12:13], v[14:15]
	v_lshl_add_u64 v[6:7], v[0:1], 0, v[6:7]
	v_pk_mul_f32 v[12:13], v[12:13], v[18:19]
	s_waitcnt vmcnt(2)
	v_lshlrev_b32_e32 v18, 16, v20
	v_cvt_pk_bf16_f32 v11, v12, v13
	v_and_b32_e32 v19, 0xffff0000, v20
	v_mul_f32_e32 v13, 0xbfb8aa3b, v18
	v_exp_f32_e32 v20, v13
	v_mul_f32_e32 v13, 0xbfb8aa3b, v19
	v_exp_f32_e32 v25, v13
	v_lshl_add_u32 v12, v26, 7, v32
	v_add_f32_e32 v20, 1.0, v20
	ds_read_b128 v[12:15], v12 offset:51200
	v_rcp_f32_e32 v24, v20
	v_add_f32_e32 v20, 1.0, v25
	v_rcp_f32_e32 v25, v20
	global_store_dwordx4 v[6:7], v[8:11], off
	s_waitcnt lgkmcnt(0)
	v_lshlrev_b32_e32 v6, 16, v12
	v_and_b32_e32 v7, 0xffff0000, v12
	v_lshlrev_b32_e32 v10, 16, v21
	v_and_b32_e32 v11, 0xffff0000, v21
	v_pk_mul_f32 v[8:9], v[24:25], v[18:19]
	v_mul_f32_e32 v12, 0xbfb8aa3b, v10
	v_mul_f32_e32 v18, 0xbfb8aa3b, v11
	v_exp_f32_e32 v12, v12
	v_exp_f32_e32 v18, v18
	v_pk_mul_f32 v[6:7], v[8:9], v[6:7]
	v_add_f32_e32 v8, 1.0, v12
	v_add_f32_e32 v9, 1.0, v18
	v_rcp_f32_e32 v8, v8
	v_rcp_f32_e32 v9, v9
	v_cvt_pk_bf16_f32 v6, v6, v7
	v_lshlrev_b32_e32 v12, 16, v13
	v_and_b32_e32 v13, 0xffff0000, v13
	v_pk_mul_f32 v[8:9], v[8:9], v[10:11]
	v_lshlrev_b32_e32 v10, 16, v22
	v_and_b32_e32 v11, 0xffff0000, v22
	v_mul_f32_e32 v7, 0xbfb8aa3b, v10
	v_exp_f32_e32 v7, v7
	v_mul_f32_e32 v18, 0xbfb8aa3b, v11
	v_exp_f32_e32 v18, v18
	v_pk_mul_f32 v[8:9], v[8:9], v[12:13]
	v_add_f32_e32 v7, 1.0, v7
	v_rcp_f32_e32 v12, v7
	v_add_f32_e32 v7, 1.0, v18
	v_rcp_f32_e32 v13, v7
	v_cvt_pk_bf16_f32 v7, v8, v9
	v_lshlrev_b32_e32 v8, 16, v14
	v_and_b32_e32 v9, 0xffff0000, v14
	v_pk_mul_f32 v[10:11], v[12:13], v[10:11]
	v_lshlrev_b32_e32 v12, 16, v23
	v_and_b32_e32 v13, 0xffff0000, v23
	v_mul_f32_e32 v14, 0xbfb8aa3b, v12
	v_mul_f32_e32 v18, 0xbfb8aa3b, v13
	v_exp_f32_e32 v14, v14
	v_exp_f32_e32 v18, v18
	v_pk_mul_f32 v[8:9], v[10:11], v[8:9]
	v_add_f32_e32 v10, 1.0, v14
	v_add_f32_e32 v11, 1.0, v18
	v_rcp_f32_e32 v10, v10
	v_rcp_f32_e32 v11, v11
	v_lshlrev_b32_e32 v14, 16, v15
	v_and_b32_e32 v15, 0xffff0000, v15
	v_cvt_pk_bf16_f32 v8, v8, v9
	v_pk_mul_f32 v[10:11], v[10:11], v[12:13]
	s_waitcnt vmcnt(1)
	v_lshlrev_b32_e32 v18, 16, v2
	v_pk_mul_f32 v[10:11], v[10:11], v[14:15]
	v_and_b32_e32 v19, 0xffff0000, v2
	v_cvt_pk_bf16_f32 v9, v10, v11
	v_lshlrev_b64 v[10:11], 11, v[26:27]
	v_mul_f32_e32 v2, 0xbfb8aa3b, v18
	v_lshl_add_u64 v[14:15], v[0:1], 0, v[10:11]
	v_exp_f32_e32 v2, v2
	v_mul_f32_e32 v11, 0xbfb8aa3b, v19
	v_exp_f32_e32 v21, v11
	v_lshl_add_u32 v10, v16, 7, v32
	ds_read_b128 v[10:13], v10 offset:51200
	v_add_f32_e32 v2, 1.0, v2
	v_rcp_f32_e32 v20, v2
	v_add_f32_e32 v2, 1.0, v21
	v_rcp_f32_e32 v21, v2
	global_store_dwordx4 v[14:15], v[6:9], off
	v_lshlrev_b32_e32 v14, 16, v3
	v_and_b32_e32 v15, 0xffff0000, v3
	v_mul_f32_e32 v2, 0xbfb8aa3b, v14
	s_waitcnt lgkmcnt(0)
	v_lshlrev_b32_e32 v6, 16, v10
	v_and_b32_e32 v7, 0xffff0000, v10
	v_exp_f32_e32 v10, v2
	v_mul_f32_e32 v2, 0xbfb8aa3b, v15
	v_pk_mul_f32 v[8:9], v[20:21], v[18:19]
	v_exp_f32_e32 v18, v2
	v_pk_mul_f32 v[2:3], v[8:9], v[6:7]
	v_add_f32_e32 v6, 1.0, v10
	v_lshlrev_b32_e32 v10, 16, v4
	v_add_f32_e32 v7, 1.0, v18
	v_cvt_pk_bf16_f32 v2, v2, v3
	v_lshlrev_b32_e32 v8, 16, v11
	v_and_b32_e32 v9, 0xffff0000, v11
	v_and_b32_e32 v11, 0xffff0000, v4
	v_mul_f32_e32 v3, 0xbfb8aa3b, v10
	v_rcp_f32_e32 v6, v6
	v_rcp_f32_e32 v7, v7
	v_exp_f32_e32 v3, v3
	v_mul_f32_e32 v4, 0xbfb8aa3b, v11
	v_exp_f32_e32 v4, v4
	v_pk_mul_f32 v[6:7], v[6:7], v[14:15]
	v_add_f32_e32 v3, 1.0, v3
	v_pk_mul_f32 v[6:7], v[6:7], v[8:9]
	v_rcp_f32_e32 v8, v3
	v_add_f32_e32 v3, 1.0, v4
	v_rcp_f32_e32 v9, v3
	v_cvt_pk_bf16_f32 v3, v6, v7
	v_lshlrev_b32_e32 v6, 16, v12
	v_and_b32_e32 v7, 0xffff0000, v12
	v_pk_mul_f32 v[8:9], v[8:9], v[10:11]
	v_lshlrev_b32_e32 v10, 16, v5
	v_and_b32_e32 v11, 0xffff0000, v5
	v_mul_f32_e32 v4, 0xbfb8aa3b, v10
	v_exp_f32_e32 v12, v4
	v_mul_f32_e32 v4, 0xbfb8aa3b, v11
	v_exp_f32_e32 v14, v4
	v_pk_mul_f32 v[4:5], v[8:9], v[6:7]
	v_add_f32_e32 v6, 1.0, v12
	v_rcp_f32_e32 v6, v6
	v_add_f32_e32 v7, 1.0, v14
	v_rcp_f32_e32 v7, v7
	v_lshlrev_b32_e32 v8, 16, v13
	v_and_b32_e32 v9, 0xffff0000, v13
	v_cvt_pk_bf16_f32 v4, v4, v5
	v_pk_mul_f32 v[6:7], v[6:7], v[10:11]
	s_nop 0
	v_pk_mul_f32 v[6:7], v[6:7], v[8:9]
	s_nop 0
	v_cvt_pk_bf16_f32 v5, v6, v7
	v_lshlrev_b64 v[6:7], 11, v[16:17]
	v_lshl_add_u64 v[0:1], v[0:1], 0, v[6:7]
	global_store_dwordx4 v[0:1], v[2:5], off
	s_and_saveexec_b64 s[6:7], vcc
	s_cbranch_execz .LBB0_226
	s_movk_i32 s1, 0x200
	v_add_u32_e32 v0, s98, v64
	v_cmp_gt_u32_e32 vcc, s1, v64
	v_mov_b32_e32 v1, s46
	s_nop 0
	v_cndmask_b32_e32 v0, -2, v0, vcc
	ds_write_b32 v1, v0
	s_branch .LBB0_226
